# v67: v63 with the GEMM main loop head on a 64-byte boundary (dead-space padding only)
# speedup vs baseline: 1.0113x; 1.0113x over previous
.LBB0_9:
	s_mul_i32 s3, s6, 3
	s_getpc_b64 s[0:1]
	s_add_u32 s0, s0, PROG@rel32@lo+4
	s_addc_u32 s1, s1, PROG@rel32@hi+12
	s_and_b32 s2, s3, -4
	s_add_u32 s0, s0, s2
	s_addc_u32 s1, s1, 0
	s_load_dwordx2 s[0:1], s[0:1], 0x0
	s_and_b32 s3, s3, 3
	s_lshl_b32 s3, s3, 3
	s_waitcnt lgkmcnt(0)
	s_lshr_b64 s[0:1], s[0:1], s3
	s_and_b32 s2, s0, 0xffff
	v_mov_b32_e32 v0, s2
	s_bfe_u32 s2, s0, 0x80010
	v_mov_b32_e32 v2, s2
	s_cmp_gt_u32 s6, 1
	s_cbranch_scc1 .Lsm_done
	v_readlane_b32 s0, v254, 39
	v_readlane_b32 s1, v254, 40
	s_add_u32 s0, s0, 0xc000
	s_addc_u32 s1, s1, 0
	s_cmp_eq_u32 s6, 1
	s_cbranch_scc1 .Lsm_cache
	s_getreg_b32 s2, hwreg(HW_REG_XCC_ID, 0, 4)
	s_and_b32 s2, s2, 15
	s_lshl_b32 s2, 1, s2
	s_and_b32 s3, s66, 7
	s_lshl_b32 s3, s3, 2
	s_add_u32 s0, s0, s3
	s_addc_u32 s1, s1, 0
	v_mov_b32_e32 v3, s2
	s_mov_b64 s[2:3], exec
	s_mov_b64 exec, 1
	global_atomic_or v1, v3, s[0:1]
	s_mov_b64 exec, s[2:3]
	s_branch .Lsm_done
	s_nop 0
	s_nop 0
	s_nop 0
	s_nop 0
	s_nop 0
	s_nop 0
	s_nop 0
.Lsm_cache:
	global_load_dwordx4 v[4:7], v1, s[0:1] sc1
	global_load_dwordx4 v[8:11], v1, s[0:1] offset:16 sc1
	s_waitcnt vmcnt(0)
	v_add_u32_e32 v3, -1, v4
	v_and_b32_e32 v3, v3, v4
	v_add_u32_e32 v4, -1, v5
	v_and_or_b32 v3, v4, v5, v3
	v_add_u32_e32 v4, -1, v6
	v_and_or_b32 v3, v4, v6, v3
	v_add_u32_e32 v4, -1, v7
	v_and_or_b32 v3, v4, v7, v3
	v_add_u32_e32 v4, -1, v8
	v_and_or_b32 v3, v4, v8, v3
	v_add_u32_e32 v4, -1, v9
	v_and_or_b32 v3, v4, v9, v3
	v_add_u32_e32 v4, -1, v10
	v_and_or_b32 v3, v4, v10, v3
	v_add_u32_e32 v4, -1, v11
	v_and_or_b32 v3, v4, v11, v3
	s_nop 0
	v_readfirstlane_b32 s2, v3
	s_nop 1
	v_writelane_b32 v255, s2, 63
